# chain step: first two kT LDS reads hoisted into free temps right after last O MFMA (S-update MFMA 1-2 no longer wait on LDS), on top of gate-read pipelining
# speedup vs baseline: 1.0029x; 1.0029x over previous
.LBB0_203:
	s_or_b64 exec, exec, s[2:3]
	v_add_u32_e32 v190, 0x2000, v224
	ds_read2_b64 v[66:69], v224 offset1:2
	ds_read2_b64 v[170:173], v224 offset0:4 offset1:6
	ds_read2_b64 v[70:73], v190 offset0:64 offset1:66
	ds_read2_b64 v[174:177], v190 offset0:68 offset1:70
	ds_read2_b64 v[178:181], v224 offset0:8 offset1:10
	ds_read2_b64 v[182:185], v190 offset0:72 offset1:74
	ds_read2_b64 v[234:237], v224 offset0:12 offset1:14
	ds_read2_b64 v[238:241], v190 offset0:76 offset1:78
	s_add_i32 s7, s8, -3
	s_and_b64 s[2:3], s[4:5], exec
	s_cselect_b32 s2, s7, s6
	s_add_i32 s2, s2, s37
	v_cvt_pk_bf16_f32 v74, v50, v51
	v_cvt_pk_bf16_f32 v75, v52, v53
	v_cvt_pk_bf16_f32 v76, v54, v55
	v_cvt_pk_bf16_f32 v77, v56, v57
	v_cvt_pk_bf16_f32 v242, v58, v59
	v_cvt_pk_bf16_f32 v243, v60, v61
	s_waitcnt lgkmcnt(7)
	v_mfma_f32_32x32x16_bf16 v[82:97], v[74:77], v[66:69], 0
	v_cvt_pk_bf16_f32 v244, v62, v63
	v_cvt_pk_bf16_f32 v245, v64, v65
	s_waitcnt lgkmcnt(5)
	v_mfma_f32_32x32x16_bf16 v[66:81], v[74:77], v[70:73], 0
	v_mfma_f32_32x32x16_bf16 v[82:97], v[242:245], v[170:173], v[82:97]
	s_waitcnt lgkmcnt(4)
	v_mfma_f32_32x32x16_bf16 v[66:81], v[242:245], v[174:177], v[66:81]
	ds_read2_b64 v[170:173], v224 offset0:16 offset1:18
	ds_read2_b64 v[174:177], v224 offset0:20 offset1:22
	ds_read2_b64 v[242:245], v190 offset0:80 offset1:82
	ds_read2_b64 v[246:249], v190 offset0:84 offset1:86
	v_cvt_pk_bf16_f32 v194, v34, v35
	v_cvt_pk_bf16_f32 v195, v36, v37
	v_cvt_pk_bf16_f32 v196, v38, v39
	v_cvt_pk_bf16_f32 v197, v40, v41
	s_waitcnt lgkmcnt(7)
	s_nop 0
	v_mfma_f32_32x32x16_bf16 v[82:97], v[194:197], v[178:181], v[82:97]
	v_cvt_pk_bf16_f32 v178, v42, v43
	v_cvt_pk_bf16_f32 v179, v44, v45
	v_cvt_pk_bf16_f32 v180, v46, v47
	v_cvt_pk_bf16_f32 v181, v48, v49
	s_waitcnt lgkmcnt(6)
	v_mfma_f32_32x32x16_bf16 v[66:81], v[194:197], v[182:185], v[66:81]
	s_waitcnt lgkmcnt(5)
	v_mfma_f32_32x32x16_bf16 v[82:97], v[178:181], v[234:237], v[82:97]
	s_waitcnt lgkmcnt(4)
	v_mfma_f32_32x32x16_bf16 v[66:81], v[178:181], v[238:241], v[66:81]
	ds_read2_b64 v[194:197], v224 offset0:24 offset1:26
	ds_read2_b64 v[234:237], v224 offset0:28 offset1:30
	ds_read2_b64 v[238:241], v190 offset0:88 offset1:90
	ds_read2_b64 v[190:193], v190 offset0:92 offset1:94
	v_cvt_pk_bf16_f32 v178, v18, v19
	v_cvt_pk_bf16_f32 v179, v20, v21
	v_cvt_pk_bf16_f32 v180, v22, v23
	v_cvt_pk_bf16_f32 v181, v24, v25
	s_waitcnt lgkmcnt(7)
	s_nop 0
	v_mfma_f32_32x32x16_bf16 v[82:97], v[178:181], v[170:173], v[82:97]
	v_cvt_pk_bf16_f32 v170, v26, v27
	v_cvt_pk_bf16_f32 v171, v28, v29
	v_cvt_pk_bf16_f32 v172, v30, v31
	v_cvt_pk_bf16_f32 v173, v32, v33
	s_waitcnt lgkmcnt(5)
	v_mfma_f32_32x32x16_bf16 v[66:81], v[178:181], v[242:245], v[66:81]
	v_mfma_f32_32x32x16_bf16 v[82:97], v[170:173], v[174:177], v[82:97]
	s_waitcnt lgkmcnt(4)
	v_mfma_f32_32x32x16_bf16 v[66:81], v[170:173], v[246:249], v[66:81]
	ds_read_b128 v[182:185], v221 offset:35840
	ds_read_b128 v[178:181], v221 offset:35872
	ds_read_b128 v[174:177], v221 offset:35904
	ds_read_b128 v[170:173], v221 offset:35936
	v_cvt_pk_bf16_f32 v242, v2, v3
	v_cvt_pk_bf16_f32 v243, v4, v5
	v_cvt_pk_bf16_f32 v244, v6, v7
	v_cvt_pk_bf16_f32 v245, v8, v9
	s_waitcnt lgkmcnt(7)
	s_nop 0
	v_mfma_f32_32x32x16_bf16 v[82:97], v[242:245], v[194:197], v[82:97]
	v_cvt_pk_bf16_f32 v194, v10, v11
	v_cvt_pk_bf16_f32 v195, v12, v13
	v_cvt_pk_bf16_f32 v196, v14, v15
	v_cvt_pk_bf16_f32 v197, v16, v17
	s_waitcnt lgkmcnt(5)
	v_mfma_f32_32x32x16_bf16 v[66:81], v[242:245], v[238:241], v[66:81]
	v_mfma_f32_32x32x16_bf16 v[82:97], v[194:197], v[234:237], v[82:97]
	s_waitcnt lgkmcnt(4)
	v_mfma_f32_32x32x16_bf16 v[66:81], v[194:197], v[190:193], v[66:81]
	ds_read_b128 v[242:245], v226 offset:17408
	ds_read_b128 v[246:249], v226 offset:17440
	ds_read_b128 v[190:193], v221 offset:35968
	ds_read_b128 v[194:197], v221 offset:36000
	ds_read_b128 v[234:237], v221 offset:36032
	ds_read_b128 v[238:241], v221 offset:36064
	s_waitcnt lgkmcnt(9)
	v_mul_f32_e32 v52, v52, v184
	v_mul_f32_e32 v53, v53, v185
	s_waitcnt lgkmcnt(8)
	v_mul_f32_e32 v56, v56, v180
	v_mul_f32_e32 v57, v57, v181
	s_waitcnt lgkmcnt(7)
	v_mul_f32_e32 v60, v60, v176
	v_mul_f32_e32 v61, v61, v177
	s_waitcnt lgkmcnt(6)
	v_mul_f32_e32 v64, v64, v172
	v_mul_f32_e32 v65, v65, v173
	v_mul_f32_e32 v62, v62, v170
	v_mul_f32_e32 v63, v63, v171
	v_mul_f32_e32 v58, v58, v174
	v_mul_f32_e32 v59, v59, v175
	v_mul_f32_e32 v54, v54, v178
	v_mul_f32_e32 v55, v55, v179
	v_mul_f32_e32 v50, v50, v182
	v_mul_f32_e32 v51, v51, v183
	ds_read_b128 v[182:185], v221 offset:36096
	ds_read_b128 v[178:181], v221 offset:36128
	ds_read_b128 v[174:177], v221 offset:36160
	ds_read_b128 v[170:173], v221 offset:36192
	s_waitcnt lgkmcnt(7)
	v_mul_f32_e32 v36, v36, v192
	v_mul_f32_e32 v37, v37, v193
	s_waitcnt lgkmcnt(6)
	v_mul_f32_e32 v40, v40, v196
	v_mul_f32_e32 v41, v41, v197
	s_waitcnt lgkmcnt(5)
	v_mul_f32_e32 v44, v44, v236
	v_mul_f32_e32 v45, v45, v237
	s_waitcnt lgkmcnt(4)
	v_mul_f32_e32 v48, v48, v240
	v_mul_f32_e32 v49, v49, v241
	v_mul_f32_e32 v46, v46, v238
	v_mul_f32_e32 v47, v47, v239
	v_mul_f32_e32 v42, v42, v234
	v_mul_f32_e32 v43, v43, v235
	v_mul_f32_e32 v38, v38, v194
	v_mul_f32_e32 v39, v39, v195
	v_mul_f32_e32 v34, v34, v190
	v_mul_f32_e32 v35, v35, v191
	ds_read_b128 v[190:193], v221 offset:36224
	ds_read_b128 v[194:197], v221 offset:36256
	ds_read_b128 v[234:237], v221 offset:36288
	ds_read_b128 v[238:241], v221 offset:36320
	s_waitcnt lgkmcnt(7)
	v_mul_f32_e32 v20, v20, v184
	v_mul_f32_e32 v21, v21, v185
	s_waitcnt lgkmcnt(6)
	v_mul_f32_e32 v24, v24, v180
	v_mul_f32_e32 v25, v25, v181
	s_waitcnt lgkmcnt(5)
	v_mul_f32_e32 v28, v28, v176
	v_mul_f32_e32 v29, v29, v177
	s_waitcnt lgkmcnt(4)
	v_mul_f32_e32 v32, v32, v172
	v_mul_f32_e32 v33, v33, v173
	v_mul_f32_e32 v30, v30, v170
	v_mul_f32_e32 v31, v31, v171
	v_mul_f32_e32 v26, v26, v174
	v_mul_f32_e32 v27, v27, v175
	v_mul_f32_e32 v22, v22, v178
	v_mul_f32_e32 v23, v23, v179
	v_mul_f32_e32 v18, v18, v182
	v_mul_f32_e32 v19, v19, v183
	ds_read_b128 v[174:177], v226 offset:17472
	ds_read_b128 v[170:173], v226 offset:17504
	s_waitcnt lgkmcnt(5)
	v_mul_f32_e32 v4, v4, v192
	v_mul_f32_e32 v5, v5, v193
	s_waitcnt lgkmcnt(4)
	v_mul_f32_e32 v8, v8, v196
	v_mul_f32_e32 v9, v9, v197
	s_waitcnt lgkmcnt(3)
	v_mul_f32_e32 v12, v12, v236
	v_mul_f32_e32 v13, v13, v237
	s_waitcnt lgkmcnt(2)
	v_mul_f32_e32 v16, v16, v240
	v_mul_f32_e32 v17, v17, v241
	v_mul_f32_e32 v14, v14, v238
	v_mul_f32_e32 v15, v15, v239
	v_mul_f32_e32 v10, v10, v234
	v_mul_f32_e32 v11, v11, v235
	v_mul_f32_e32 v6, v6, v194
	v_mul_f32_e32 v7, v7, v195
	v_mul_f32_e32 v2, v2, v190
	v_mul_f32_e32 v3, v3, v191
	ds_read_b128 v[190:193], v227 offset:17408
	ds_read_b128 v[194:197], v227 offset:17440
	ds_read_b128 v[234:237], v227 offset:17472
	ds_read_b128 v[238:241], v227 offset:17504
	s_waitcnt vmcnt(15)
	v_mfma_f32_32x32x16_bf16 v[50:65], v[242:245], v[114:117], v[50:65]
	s_waitcnt vmcnt(14)
	v_mfma_f32_32x32x16_bf16 v[50:65], v[246:249], v[110:113], v[50:65]
	s_waitcnt vmcnt(13) lgkmcnt(5)
	v_mfma_f32_32x32x16_bf16 v[50:65], v[174:177], v[106:109], v[50:65]
	s_waitcnt vmcnt(12) lgkmcnt(4)
	v_mfma_f32_32x32x16_bf16 v[50:65], v[170:173], v[102:105], v[50:65]
	v_lshl_or_b32 v242, s2, 6, v219
	v_ashrrev_i32_e32 v243, 31, v242
	v_lshlrev_b64 v[244:245], 11, v[242:243]
	v_lshl_add_u64 v[244:245], v[202:203], 0, v[244:245]
	v_cvt_pk_bf16_f32 v82, v82, v83
	v_cvt_pk_bf16_f32 v83, v84, v85
	v_cvt_pk_bf16_f32 v84, v90, v91
	v_cvt_pk_bf16_f32 v85, v92, v93
	v_cvt_pk_bf16_f32 v86, v86, v87
	v_cvt_pk_bf16_f32 v87, v88, v89
	v_cvt_pk_bf16_f32 v88, v94, v95
	v_cvt_pk_bf16_f32 v89, v96, v97
	v_or_b32_e32 v90, 32, v242
	v_ashrrev_i32_e32 v91, 31, v90
	v_permlane32_swap_b32_e32 v82, v84
	v_permlane32_swap_b32_e32 v83, v85
	v_permlane32_swap_b32_e32 v86, v88
	v_permlane32_swap_b32_e32 v87, v89
	global_store_dwordx4 v[244:245], v[82:85], off
	global_store_dwordx4 v[244:245], v[86:89], off offset:16
	v_lshlrev_b64 v[90:91], 11, v[90:91]
	v_lshl_add_u64 v[90:91], v[202:203], 0, v[90:91]
	v_cvt_pk_bf16_f32 v66, v66, v67
	v_cvt_pk_bf16_f32 v67, v68, v69
	v_cvt_pk_bf16_f32 v68, v74, v75
	v_cvt_pk_bf16_f32 v69, v76, v77
	v_cvt_pk_bf16_f32 v70, v70, v71
	v_cvt_pk_bf16_f32 v71, v72, v73
	v_cvt_pk_bf16_f32 v72, v78, v79
	v_cvt_pk_bf16_f32 v73, v80, v81
	s_nop 1
	v_permlane32_swap_b32_e32 v66, v68
	v_permlane32_swap_b32_e32 v67, v69
	v_permlane32_swap_b32_e32 v70, v72
	v_permlane32_swap_b32_e32 v71, v73
	global_store_dwordx4 v[90:91], v[66:69], off
	global_store_dwordx4 v[90:91], v[70:73], off offset:16
	s_waitcnt vmcnt(15)
	ds_write_b128 v187, v[118:121] offset:36864
	s_waitcnt vmcnt(14)
	ds_write_b128 v187, v[122:125] offset:45568
	s_waitcnt vmcnt(13)
	ds_write_b128 v220, v[130:133] offset:54272
	s_waitcnt vmcnt(12)
	ds_write_b128 v220, v[134:137] offset:63488
	s_and_saveexec_b64 s[14:15], vcc
	v_add_u32_e32 v66, 0x11c00, v228
	ds_write_b128 v66, v[126:129]
	s_or_b64 exec, exec, s[14:15]
	ds_read_b128 v[170:173], v225 offset:26624
	ds_read_b128 v[174:177], v225 offset:26656
	ds_read_b128 v[178:181], v225 offset:26688
	ds_read_b128 v[182:185], v225 offset:26720
	s_waitcnt lgkmcnt(7)
	v_mfma_f32_32x32x16_bf16 v[34:49], v[190:193], v[114:117], v[34:49]
	s_waitcnt lgkmcnt(6)
	v_mfma_f32_32x32x16_bf16 v[34:49], v[194:197], v[110:113], v[34:49]
	s_waitcnt lgkmcnt(5)
	v_mfma_f32_32x32x16_bf16 v[34:49], v[234:237], v[106:109], v[34:49]
	s_waitcnt lgkmcnt(4)
	v_mfma_f32_32x32x16_bf16 v[34:49], v[238:241], v[102:105], v[34:49]
	ds_read_b128 v[190:193], v225 offset:31232
	ds_read_b128 v[194:197], v225 offset:31264
	ds_read_b128 v[234:237], v225 offset:31296
	ds_read_b128 v[238:241], v225 offset:31328
	s_waitcnt lgkmcnt(7)
	v_mfma_f32_32x32x16_bf16 v[18:33], v[170:173], v[114:117], v[18:33]
	s_waitcnt lgkmcnt(6)
	v_mfma_f32_32x32x16_bf16 v[18:33], v[174:177], v[110:113], v[18:33]
	s_waitcnt lgkmcnt(5)
	v_mfma_f32_32x32x16_bf16 v[18:33], v[178:181], v[106:109], v[18:33]
	s_waitcnt lgkmcnt(4)
	v_mfma_f32_32x32x16_bf16 v[18:33], v[182:185], v[102:105], v[18:33]
	s_waitcnt lgkmcnt(3)
	v_mfma_f32_32x32x16_bf16 v[2:17], v[190:193], v[114:117], v[2:17]
	s_waitcnt lgkmcnt(2)
	v_mfma_f32_32x32x16_bf16 v[2:17], v[194:197], v[110:113], v[2:17]
	s_waitcnt lgkmcnt(1)
	v_mfma_f32_32x32x16_bf16 v[2:17], v[234:237], v[106:109], v[2:17]
	s_waitcnt lgkmcnt(0)
	v_mfma_f32_32x32x16_bf16 v[2:17], v[238:241], v[102:105], v[2:17]
	s_lshl_b64 s[0:1], s[0:1], 15
	v_lshl_add_u64 v[102:103], v[206:207], 0, s[0:1]
	global_load_dwordx4 v[114:117], v[102:103], off
	global_load_dwordx4 v[110:113], v[102:103], off offset:32
	global_load_dwordx4 v[106:109], v[102:103], off offset:64
	s_nop 0
	global_load_dwordx4 v[102:105], v[102:103], off offset:96
	v_mov_b32_e32 v66, s8
	s_min_u32 s2, s8, s52
	v_sub_u32_e64 v66, s52, v66 clamp
	s_and_b64 s[0:1], s[4:5], exec
	v_readfirstlane_b32 s0, v66
	s_cselect_b32 s0, s2, s0
	s_add_i32 s2, s0, s37
	v_lshl_add_u32 v68, s2, 6, v218
	v_mad_i64_i32 v[66:67], s[0:1], v68, s28, v[200:201]
	v_add_u32_e32 v68, 32, v68
	v_mad_i64_i32 v[68:69], s[0:1], v68, s28, v[200:201]
	s_lshl_b32 s0, s2, 2
	s_or_b32 s0, s0, s12
	s_ashr_i32 s1, s0, 31
	s_lshl_b64 s[2:3], s[0:1], 14
	s_add_u32 s2, s36, s2
	s_addc_u32 s3, s13, s3
	s_waitcnt lgkmcnt(0)
	s_barrier
	global_load_dwordx4 v[118:121], v[66:67], off
	global_load_dwordx4 v[122:125], v[68:69], off
	v_lshl_add_u64 v[66:67], v[188:189], 1, s[2:3]
	v_lshl_add_u64 v[66:67], v[66:67], 0, v[0:1]
	v_lshl_add_u64 v[68:69], v[198:199], 1, s[2:3]
	v_lshl_add_u64 v[68:69], v[68:69], 0, v[0:1]
	global_load_dwordx4 v[130:133], v[66:67], off
	global_load_dwordx4 v[134:137], v[68:69], off
	s_and_saveexec_b64 s[2:3], vcc
	s_cbranch_execz .LBB0_207
	s_lshl_b64 s[14:15], s[0:1], 9
	v_lshl_add_u64 v[66:67], v[204:205], 0, s[14:15]
	global_load_dwordx4 v[126:129], v[66:67], off
.LBB0_207:
	s_or_b64 exec, exec, s[2:3]
	v_add_u32_e32 v229, 0x9000, v224
	v_add_u32_e32 v246, 0xb000, v224
	ds_read2_b64 v[66:69], v229 offset1:2
	ds_read2_b64 v[170:173], v229 offset0:4 offset1:6
	ds_read2_b64 v[70:73], v246 offset0:64 offset1:66
	ds_read2_b64 v[174:177], v246 offset0:68 offset1:70
	ds_read2_b64 v[178:181], v229 offset0:8 offset1:10
	ds_read2_b64 v[182:185], v246 offset0:72 offset1:74
	ds_read2_b64 v[190:193], v229 offset0:12 offset1:14
	ds_read2_b64 v[194:197], v246 offset0:76 offset1:78
	s_xor_b32 s2, s7, 0x3fffffe
	s_add_i32 s3, s2, s81
	s_add_i32 s2, s7, 1
	s_and_b64 s[14:15], s[4:5], exec
	s_cselect_b32 s3, s2, s3
	s_add_i32 s3, s3, s37
	v_cvt_pk_bf16_f32 v74, v50, v51
	v_cvt_pk_bf16_f32 v75, v52, v53
	v_cvt_pk_bf16_f32 v76, v54, v55
	v_cvt_pk_bf16_f32 v77, v56, v57
	v_cvt_pk_bf16_f32 v234, v58, v59
	v_cvt_pk_bf16_f32 v235, v60, v61
	s_waitcnt lgkmcnt(7)
	v_mfma_f32_32x32x16_bf16 v[82:97], v[74:77], v[66:69], 0
	v_cvt_pk_bf16_f32 v236, v62, v63
	v_cvt_pk_bf16_f32 v237, v64, v65
	s_waitcnt lgkmcnt(5)
	v_mfma_f32_32x32x16_bf16 v[66:81], v[74:77], v[70:73], 0
	v_mfma_f32_32x32x16_bf16 v[82:97], v[234:237], v[170:173], v[82:97]
	s_waitcnt lgkmcnt(4)
	v_mfma_f32_32x32x16_bf16 v[66:81], v[234:237], v[174:177], v[66:81]
	ds_read2_b64 v[170:173], v229 offset0:16 offset1:18
	ds_read2_b64 v[174:177], v229 offset0:20 offset1:22
	ds_read2_b64 v[234:237], v246 offset0:80 offset1:82
	ds_read2_b64 v[238:241], v246 offset0:84 offset1:86
	v_cvt_pk_bf16_f32 v242, v34, v35
	v_cvt_pk_bf16_f32 v243, v36, v37
	v_cvt_pk_bf16_f32 v244, v38, v39
	v_cvt_pk_bf16_f32 v245, v40, v41
	s_waitcnt lgkmcnt(7)
	s_nop 0
	v_mfma_f32_32x32x16_bf16 v[82:97], v[242:245], v[178:181], v[82:97]
	v_cvt_pk_bf16_f32 v178, v42, v43
	v_cvt_pk_bf16_f32 v179, v44, v45
	v_cvt_pk_bf16_f32 v180, v46, v47
	v_cvt_pk_bf16_f32 v181, v48, v49
	s_waitcnt lgkmcnt(6)
	v_mfma_f32_32x32x16_bf16 v[66:81], v[242:245], v[182:185], v[66:81]
	s_waitcnt lgkmcnt(5)
	v_mfma_f32_32x32x16_bf16 v[82:97], v[178:181], v[190:193], v[82:97]
	s_waitcnt lgkmcnt(4)
	v_mfma_f32_32x32x16_bf16 v[66:81], v[178:181], v[194:197], v[66:81]
	ds_read2_b64 v[190:193], v229 offset0:24 offset1:26
	ds_read2_b64 v[194:197], v229 offset0:28 offset1:30
	ds_read2_b64 v[242:245], v246 offset0:88 offset1:90
	ds_read2_b64 v[246:249], v246 offset0:92 offset1:94
	v_cvt_pk_bf16_f32 v178, v18, v19
	v_cvt_pk_bf16_f32 v179, v20, v21
	v_cvt_pk_bf16_f32 v180, v22, v23
	v_cvt_pk_bf16_f32 v181, v24, v25
	s_waitcnt lgkmcnt(7)
	s_nop 0
	v_mfma_f32_32x32x16_bf16 v[82:97], v[178:181], v[170:173], v[82:97]
	v_cvt_pk_bf16_f32 v170, v26, v27
	v_cvt_pk_bf16_f32 v171, v28, v29
	v_cvt_pk_bf16_f32 v172, v30, v31
	v_cvt_pk_bf16_f32 v173, v32, v33
	s_waitcnt lgkmcnt(5)
	v_mfma_f32_32x32x16_bf16 v[66:81], v[178:181], v[234:237], v[66:81]
	v_mfma_f32_32x32x16_bf16 v[82:97], v[170:173], v[174:177], v[82:97]
	s_waitcnt lgkmcnt(4)
	v_mfma_f32_32x32x16_bf16 v[66:81], v[170:173], v[238:241], v[66:81]
	v_add_u32_e32 v229, 0x11c00, v186
	ds_read_b128 v[182:185], v229
	ds_read_b128 v[178:181], v229 offset:32
	ds_read_b128 v[174:177], v229 offset:64
	ds_read_b128 v[170:173], v229 offset:96
	v_cvt_pk_bf16_f32 v234, v2, v3
	v_cvt_pk_bf16_f32 v235, v4, v5
	v_cvt_pk_bf16_f32 v236, v6, v7
	v_cvt_pk_bf16_f32 v237, v8, v9
	s_waitcnt lgkmcnt(7)
	s_nop 0
	v_mfma_f32_32x32x16_bf16 v[82:97], v[234:237], v[190:193], v[82:97]
	v_cvt_pk_bf16_f32 v190, v10, v11
	v_cvt_pk_bf16_f32 v191, v12, v13
	v_cvt_pk_bf16_f32 v192, v14, v15
	v_cvt_pk_bf16_f32 v193, v16, v17
	s_waitcnt lgkmcnt(5)
	v_mfma_f32_32x32x16_bf16 v[66:81], v[234:237], v[242:245], v[66:81]
	v_mfma_f32_32x32x16_bf16 v[82:97], v[190:193], v[194:197], v[82:97]
	s_waitcnt lgkmcnt(4)
	v_mfma_f32_32x32x16_bf16 v[66:81], v[190:193], v[246:249], v[66:81]
	ds_read_b128 v[242:245], v226 offset:54272
	ds_read_b128 v[246:249], v226 offset:54304
	ds_read_b128 v[190:193], v229 offset:128
	ds_read_b128 v[194:197], v229 offset:160
	ds_read_b128 v[234:237], v229 offset:192
	ds_read_b128 v[238:241], v229 offset:224
	s_waitcnt lgkmcnt(9)
	v_mul_f32_e32 v52, v52, v184
	v_mul_f32_e32 v53, v53, v185
	s_waitcnt lgkmcnt(8)
	v_mul_f32_e32 v54, v54, v178
	v_mul_f32_e32 v55, v55, v179
	s_waitcnt lgkmcnt(7)
	v_mul_f32_e32 v58, v58, v174
	v_mul_f32_e32 v59, v59, v175
	s_waitcnt lgkmcnt(6)
	v_mul_f32_e32 v62, v62, v170
	v_mul_f32_e32 v63, v63, v171
	v_mul_f32_e32 v64, v64, v172
	v_mul_f32_e32 v65, v65, v173
	v_mul_f32_e32 v60, v60, v176
	v_mul_f32_e32 v61, v61, v177
	v_mul_f32_e32 v56, v56, v180
	v_mul_f32_e32 v57, v57, v181
	v_mul_f32_e32 v50, v50, v182
	v_mul_f32_e32 v51, v51, v183
	ds_read_b128 v[182:185], v229 offset:256
	ds_read_b128 v[178:181], v229 offset:288
	ds_read_b128 v[174:177], v229 offset:320
	ds_read_b128 v[170:173], v229 offset:352
	s_waitcnt lgkmcnt(7)
	v_mul_f32_e32 v36, v36, v192
	v_mul_f32_e32 v37, v37, v193
	s_waitcnt lgkmcnt(6)
	v_mul_f32_e32 v38, v38, v194
	v_mul_f32_e32 v39, v39, v195
	s_waitcnt lgkmcnt(5)
	v_mul_f32_e32 v42, v42, v234
	v_mul_f32_e32 v43, v43, v235
	s_waitcnt lgkmcnt(4)
	v_mul_f32_e32 v46, v46, v238
	v_mul_f32_e32 v47, v47, v239
	v_mul_f32_e32 v48, v48, v240
	v_mul_f32_e32 v49, v49, v241
	v_mul_f32_e32 v44, v44, v236
	v_mul_f32_e32 v45, v45, v237
	v_mul_f32_e32 v40, v40, v196
	v_mul_f32_e32 v41, v41, v197
	v_mul_f32_e32 v34, v34, v190
	v_mul_f32_e32 v35, v35, v191
	ds_read_b128 v[190:193], v229 offset:384
	ds_read_b128 v[194:197], v229 offset:416
	ds_read_b128 v[234:237], v229 offset:448
	ds_read_b128 v[238:241], v229 offset:480
	s_waitcnt lgkmcnt(7)
	v_mul_f32_e32 v20, v20, v184
	v_mul_f32_e32 v21, v21, v185
	s_waitcnt lgkmcnt(6)
	v_mul_f32_e32 v22, v22, v178
	v_mul_f32_e32 v23, v23, v179
	s_waitcnt lgkmcnt(5)
	v_mul_f32_e32 v26, v26, v174
	v_mul_f32_e32 v27, v27, v175
	s_waitcnt lgkmcnt(4)
	v_mul_f32_e32 v30, v30, v170
	v_mul_f32_e32 v31, v31, v171
	v_mul_f32_e32 v32, v32, v172
	v_mul_f32_e32 v33, v33, v173
	v_mul_f32_e32 v28, v28, v176
	v_mul_f32_e32 v29, v29, v177
	v_mul_f32_e32 v24, v24, v180
	v_mul_f32_e32 v25, v25, v181
	v_mul_f32_e32 v18, v18, v182
	v_mul_f32_e32 v19, v19, v183
	ds_read_b128 v[174:177], v226 offset:54336
	ds_read_b128 v[170:173], v226 offset:54368
	s_waitcnt lgkmcnt(5)
	v_mul_f32_e32 v4, v4, v192
	v_mul_f32_e32 v5, v5, v193
	s_waitcnt lgkmcnt(4)
	v_mul_f32_e32 v6, v6, v194
	v_mul_f32_e32 v7, v7, v195
	s_waitcnt lgkmcnt(3)
	v_mul_f32_e32 v10, v10, v234
	v_mul_f32_e32 v11, v11, v235
	s_waitcnt lgkmcnt(2)
	v_mul_f32_e32 v14, v14, v238
	v_mul_f32_e32 v15, v15, v239
	v_mul_f32_e32 v16, v16, v240
	v_mul_f32_e32 v17, v17, v241
	v_mul_f32_e32 v12, v12, v236
	v_mul_f32_e32 v13, v13, v237
	v_mul_f32_e32 v8, v8, v196
	v_mul_f32_e32 v9, v9, v197
	v_mul_f32_e32 v2, v2, v190
	v_mul_f32_e32 v3, v3, v191
	ds_read_b128 v[190:193], v227 offset:54272
	ds_read_b128 v[194:197], v227 offset:54304
	ds_read_b128 v[234:237], v227 offset:54336
	ds_read_b128 v[238:241], v227 offset:54368
	s_waitcnt vmcnt(19)
	v_mfma_f32_32x32x16_bf16 v[50:65], v[242:245], v[150:153], v[50:65]
	s_waitcnt vmcnt(18)
	v_mfma_f32_32x32x16_bf16 v[50:65], v[246:249], v[146:149], v[50:65]
	s_waitcnt vmcnt(17) lgkmcnt(5)
	v_mfma_f32_32x32x16_bf16 v[50:65], v[174:177], v[142:145], v[50:65]
	s_waitcnt vmcnt(16) lgkmcnt(4)
	v_mfma_f32_32x32x16_bf16 v[50:65], v[170:173], v[138:141], v[50:65]
	v_lshl_or_b32 v242, s3, 6, v219
	v_ashrrev_i32_e32 v243, 31, v242
	v_lshlrev_b64 v[244:245], 11, v[242:243]
	v_lshl_add_u64 v[244:245], v[202:203], 0, v[244:245]
	v_cvt_pk_bf16_f32 v82, v82, v83
	v_cvt_pk_bf16_f32 v83, v84, v85
	v_cvt_pk_bf16_f32 v84, v90, v91
	v_cvt_pk_bf16_f32 v85, v92, v93
	v_cvt_pk_bf16_f32 v86, v86, v87
	v_cvt_pk_bf16_f32 v87, v88, v89
	v_cvt_pk_bf16_f32 v88, v94, v95
	v_cvt_pk_bf16_f32 v89, v96, v97
	v_or_b32_e32 v90, 32, v242
	v_ashrrev_i32_e32 v91, 31, v90
	v_permlane32_swap_b32_e32 v82, v84
	v_permlane32_swap_b32_e32 v83, v85
	v_permlane32_swap_b32_e32 v86, v88
	v_permlane32_swap_b32_e32 v87, v89
	global_store_dwordx4 v[244:245], v[82:85], off
	global_store_dwordx4 v[244:245], v[86:89], off offset:16
	v_lshlrev_b64 v[90:91], 11, v[90:91]
	v_lshl_add_u64 v[90:91], v[202:203], 0, v[90:91]
	v_cvt_pk_bf16_f32 v66, v66, v67
	v_cvt_pk_bf16_f32 v67, v68, v69
	v_cvt_pk_bf16_f32 v68, v74, v75
	v_cvt_pk_bf16_f32 v69, v76, v77
	v_cvt_pk_bf16_f32 v70, v70, v71
	v_cvt_pk_bf16_f32 v71, v72, v73
	v_cvt_pk_bf16_f32 v72, v78, v79
	v_cvt_pk_bf16_f32 v73, v80, v81
	s_nop 1
	v_permlane32_swap_b32_e32 v66, v68
	v_permlane32_swap_b32_e32 v67, v69
	v_permlane32_swap_b32_e32 v70, v72
	v_permlane32_swap_b32_e32 v71, v73
	global_store_dwordx4 v[90:91], v[66:69], off
	global_store_dwordx4 v[90:91], v[70:73], off offset:16
	s_waitcnt vmcnt(19)
	ds_write_b128 v187, v[154:157]
	s_waitcnt vmcnt(18)
	ds_write_b128 v187, v[158:161] offset:8704
	s_waitcnt vmcnt(17)
	ds_write_b128 v220, v[162:165] offset:17408
	s_waitcnt vmcnt(16)
	ds_write_b128 v220, v[166:169] offset:26624
	s_and_saveexec_b64 s[14:15], vcc
	ds_write_b128 v228, v[98:101] offset:35840
	s_or_b64 exec, exec, s[14:15]
	ds_read_b128 v[170:173], v222 offset:63488
	ds_read_b128 v[174:177], v222 offset:63520
	ds_read_b128 v[178:181], v222 offset:63552
	ds_read_b128 v[182:185], v222 offset:63584
	s_waitcnt lgkmcnt(7)
	v_mfma_f32_32x32x16_bf16 v[34:49], v[190:193], v[150:153], v[34:49]
	s_waitcnt lgkmcnt(6)
	v_mfma_f32_32x32x16_bf16 v[34:49], v[194:197], v[146:149], v[34:49]
	s_waitcnt lgkmcnt(5)
	v_mfma_f32_32x32x16_bf16 v[34:49], v[234:237], v[142:145], v[34:49]
	s_waitcnt lgkmcnt(4)
	v_mfma_f32_32x32x16_bf16 v[34:49], v[238:241], v[138:141], v[34:49]
	ds_read_b128 v[190:193], v223 offset:13824
	ds_read_b128 v[194:197], v223 offset:13856
	ds_read_b128 v[234:237], v223 offset:13888
	ds_read_b128 v[238:241], v223 offset:13920
	s_waitcnt lgkmcnt(7)
	v_mfma_f32_32x32x16_bf16 v[18:33], v[170:173], v[150:153], v[18:33]
	s_waitcnt lgkmcnt(6)
	v_mfma_f32_32x32x16_bf16 v[18:33], v[174:177], v[146:149], v[18:33]
	s_waitcnt lgkmcnt(5)
	v_mfma_f32_32x32x16_bf16 v[18:33], v[178:181], v[142:145], v[18:33]
	s_waitcnt lgkmcnt(4)
	v_mfma_f32_32x32x16_bf16 v[18:33], v[182:185], v[138:141], v[18:33]
	s_waitcnt lgkmcnt(3)
	v_mfma_f32_32x32x16_bf16 v[2:17], v[190:193], v[150:153], v[2:17]
	s_waitcnt lgkmcnt(2)
	v_mfma_f32_32x32x16_bf16 v[2:17], v[194:197], v[146:149], v[2:17]
	s_waitcnt lgkmcnt(1)
	v_mfma_f32_32x32x16_bf16 v[2:17], v[234:237], v[142:145], v[2:17]
	s_waitcnt lgkmcnt(0)
	v_mfma_f32_32x32x16_bf16 v[2:17], v[238:241], v[138:141], v[2:17]
	s_lshl_b64 s[0:1], s[0:1], 15
	v_lshl_add_u64 v[138:139], v[206:207], 0, s[0:1]
	global_load_dwordx4 v[150:153], v[138:139], off
	global_load_dwordx4 v[146:149], v[138:139], off offset:32
	global_load_dwordx4 v[142:145], v[138:139], off offset:64
	s_nop 0
	global_load_dwordx4 v[138:141], v[138:139], off offset:96
	s_branch .LBB0_200
